# wave_sum reductions in the three norm phases: ds_bpermute butterflies replaced by DPP row reductions + v_permlane16/32_swap
# baseline (speedup 1.0000x reference)
.LBB0_141:
	s_or_b64 exec, exec, s[6:7]
	s_load_dwordx16 s[12:27], s[86:87], 0x100
	v_lshrrev_b32_e32 v11, 10, v16
	v_add_u32_e32 v11, 1, v11
	v_cndmask_b32_e64 v11, v11, 0, vcc
	s_movk_i32 s6, 0x3000
	s_waitcnt lgkmcnt(0)
	v_mov_b64_e32 v[16:17], s[20:21]
	v_mad_u64_u32 v[16:17], s[6:7], v11, s6, v[16:17]
	s_mov_b64 s[6:7], 0x1000
	s_nop 0
	v_lshl_add_u64 v[78:79], v[16:17], 0, s[6:7]
	v_mov_b32_e32 v11, v3
	v_mov_b32_e32 v13, v3
	v_mov_b32_e32 v15, v3
	v_lshl_add_u64 v[66:67], v[18:19], 0, v[2:3]
	v_lshl_add_u64 v[74:75], v[16:17], 0, v[2:3]
	v_lshl_add_u64 v[46:47], v[78:79], 0, v[2:3]
	v_lshl_add_u64 v[50:51], v[78:79], 0, v[10:11]
	v_lshl_add_u64 v[80:81], v[78:79], 0, v[12:13]
	v_lshl_add_u64 v[82:83], v[78:79], 0, v[14:15]
	global_load_dwordx4 v[16:19], v[66:67], off
	global_load_dwordx4 v[34:37], v[66:67], off offset:1024
	global_load_dwordx4 v[38:41], v[74:75], off
	global_load_dwordx4 v[42:45], v[74:75], off offset:1024
	s_nop 0
	global_load_dwordx4 v[46:49], v[46:47], off
	s_nop 0
	global_load_dwordx4 v[50:53], v[50:51], off
	s_nop 0
	global_load_dwordx4 v[54:57], v[6:7], off
	global_load_dwordx4 v[58:61], v[6:7], off offset:1024
	global_load_dwordx4 v[62:65], v[66:67], off offset:2048
	s_nop 0
	global_load_dwordx4 v[66:69], v[66:67], off offset:3072
	s_nop 0
	global_load_dwordx4 v[70:73], v[74:75], off offset:2048
	s_nop 0
	global_load_dwordx4 v[74:77], v[74:75], off offset:3072
	s_nop 0
	global_load_dwordx4 v[78:81], v[80:81], off
	s_nop 0
	global_load_dwordx4 v[82:85], v[82:83], off
	s_nop 0
	global_load_dwordx4 v[86:89], v[6:7], off offset:2048
	global_load_dwordx4 v[90:93], v[6:7], off offset:3072
	s_waitcnt vmcnt(15)
	v_mov_b32_e32 v96, v17
	s_waitcnt vmcnt(14)
	v_mov_b32_e32 v97, v35
	v_mov_b32_e32 v94, v16
	v_mov_b32_e32 v95, v34
	v_pk_mul_f32 v[96:97], v[96:97], v[96:97]
	s_waitcnt vmcnt(7)
	v_mov_b32_e32 v98, v63
	v_pk_fma_f32 v[94:95], v[94:95], v[94:95], v[96:97]
	v_mov_b32_e32 v96, v18
	v_mov_b32_e32 v97, v36
	v_pk_fma_f32 v[94:95], v[96:97], v[96:97], v[94:95]
	v_mov_b32_e32 v96, v19
	v_mov_b32_e32 v97, v37
	s_waitcnt vmcnt(6)
	v_mov_b32_e32 v99, v67
	v_pk_fma_f32 v[94:95], v[96:97], v[96:97], v[94:95]
	v_mov_b32_e32 v96, v62
	v_mov_b32_e32 v97, v66
	v_pk_mul_f32 v[98:99], v[98:99], v[98:99]
	v_add_f32_e32 v11, v94, v95
	v_pk_fma_f32 v[96:97], v[96:97], v[96:97], v[98:99]
	v_mov_b32_e32 v98, v64
	v_mov_b32_e32 v99, v68
	v_pk_fma_f32 v[96:97], v[98:99], v[98:99], v[96:97]
	v_mov_b32_e32 v98, v65
	v_mov_b32_e32 v99, v69
	v_pk_fma_f32 v[96:97], v[98:99], v[98:99], v[96:97]
	s_mov_b32 s6, 0x800000
	v_add_f32_e32 v11, v11, v96
	v_add_f32_e32 v11, v11, v97
	s_nop 1
	v_add_f32_dpp v250, v11, v11 quad_perm:[1,0,3,2] row_mask:0xf bank_mask:0xf
	s_nop 1
	v_add_f32_dpp v250, v250, v250 quad_perm:[2,3,0,1] row_mask:0xf bank_mask:0xf
	s_nop 1
	v_add_f32_dpp v250, v250, v250 row_half_mirror row_mask:0xf bank_mask:0xf
	s_nop 1
	v_add_f32_dpp v250, v250, v250 row_mirror row_mask:0xf bank_mask:0xf
	v_mov_b32_e32 v251, v250
	v_mov_b32_e32 v252, v250
	s_nop 1
	v_permlane16_swap_b32_e32 v251, v252
	v_add_f32_e32 v250, v251, v252
	v_mov_b32_e32 v251, v250
	v_mov_b32_e32 v252, v250
	s_nop 1
	v_permlane32_swap_b32_e32 v251, v252
	v_pk_add_f32 v[48:49], v[48:49], 1.0 op_sel_hi:[1,0]
	v_pk_add_f32 v[46:47], v[46:47], 1.0 op_sel_hi:[1,0]
	s_waitcnt lgkmcnt(0)
	s_waitcnt lgkmcnt(0)
	s_waitcnt lgkmcnt(0)
	s_waitcnt lgkmcnt(0)
	s_waitcnt lgkmcnt(0)
	s_waitcnt lgkmcnt(0)
	v_add_f32_e32 v11, v251, v252
	v_fmamk_f32 v11, v11, 0x3a800000, v1
	v_mul_f32_e32 v13, 0x4b800000, v11
	v_cmp_gt_f32_e32 vcc, s6, v11
	s_nop 1
	v_cndmask_b32_e32 v11, v11, v13, vcc
	v_rsq_f32_e32 v11, v11
	s_nop 0
	v_mul_f32_e32 v13, 0x45800000, v11
	v_cndmask_b32_e32 v94, v11, v13, vcc
	v_pk_mul_f32 v[18:19], v[18:19], v[94:95] op_sel_hi:[1,0]
	v_pk_mul_f32 v[16:17], v[16:17], v[94:95] op_sel_hi:[1,0]
	v_pk_mul_f32 v[18:19], v[56:57], v[18:19]
	v_pk_mul_f32 v[16:17], v[54:55], v[16:17]
	v_pk_fma_f32 v[18:19], v[48:49], v[18:19], v[40:41]
	v_pk_fma_f32 v[16:17], v[46:47], v[16:17], v[38:39]
	v_pk_mul_f32 v[34:35], v[34:35], v[94:95] op_sel_hi:[1,0]
	v_cvt_pk_bf16_f32 v16, v16, v17
	v_cvt_pk_bf16_f32 v17, v18, v19
	v_mad_u64_u32 v[18:19], s[6:7], v4, s10, v[8:9]
	v_mov_b32_e32 v38, v19
	v_mad_u64_u32 v[38:39], s[6:7], v5, s10, v[38:39]
	v_mov_b32_e32 v19, v38
	global_store_dwordx2 v[18:19], v[16:17], off
	v_pk_mul_f32 v[16:17], v[36:37], v[94:95] op_sel_hi:[1,0]
	v_pk_mul_f32 v[34:35], v[58:59], v[34:35]
	v_pk_mul_f32 v[16:17], v[60:61], v[16:17]
	v_pk_add_f32 v[36:37], v[52:53], 1.0 op_sel_hi:[1,0]
	v_pk_add_f32 v[38:39], v[50:51], 1.0 op_sel_hi:[1,0]
	v_pk_fma_f32 v[16:17], v[36:37], v[16:17], v[44:45]
	v_pk_fma_f32 v[34:35], v[38:39], v[34:35], v[42:43]
	s_waitcnt vmcnt(4)
	v_pk_add_f32 v[36:37], v[80:81], 1.0 op_sel_hi:[1,0]
	v_cvt_pk_bf16_f32 v34, v34, v35
	v_cvt_pk_bf16_f32 v35, v16, v17
	global_store_dwordx2 v[18:19], v[34:35], off offset:512
	v_pk_mul_f32 v[16:17], v[64:65], v[94:95] op_sel_hi:[1,0]
	v_pk_mul_f32 v[34:35], v[62:63], v[94:95] op_sel_hi:[1,0]
	s_waitcnt vmcnt(3)
	v_pk_mul_f32 v[16:17], v[88:89], v[16:17]
	v_pk_mul_f32 v[34:35], v[86:87], v[34:35]
	v_pk_add_f32 v[38:39], v[78:79], 1.0 op_sel_hi:[1,0]
	v_pk_fma_f32 v[16:17], v[36:37], v[16:17], v[72:73]
	v_pk_fma_f32 v[34:35], v[38:39], v[34:35], v[70:71]
	v_pk_add_f32 v[36:37], v[84:85], 1.0 op_sel_hi:[1,0]
	v_cvt_pk_bf16_f32 v34, v34, v35
	v_cvt_pk_bf16_f32 v35, v16, v17
	global_store_dwordx2 v[18:19], v[34:35], off offset:1024
	v_pk_mul_f32 v[16:17], v[68:69], v[94:95] op_sel_hi:[1,0]
	v_pk_mul_f32 v[34:35], v[66:67], v[94:95] op_sel_hi:[1,0]
	s_waitcnt vmcnt(3)
	v_pk_mul_f32 v[16:17], v[92:93], v[16:17]
	v_pk_mul_f32 v[34:35], v[90:91], v[34:35]
	v_pk_add_f32 v[38:39], v[82:83], 1.0 op_sel_hi:[1,0]
	v_add_u32_e32 v4, s11, v4
	s_movk_i32 s6, 0x1fff
	v_pk_fma_f32 v[16:17], v[36:37], v[16:17], v[76:77]
	v_pk_fma_f32 v[34:35], v[38:39], v[34:35], v[74:75]
	v_cmp_lt_i32_e32 vcc, s6, v4
	v_cvt_pk_bf16_f32 v34, v34, v35
	v_cvt_pk_bf16_f32 v35, v16, v17
	s_or_b64 s[4:5], vcc, s[4:5]
	global_store_dwordx2 v[18:19], v[34:35], off offset:1536
	s_andn2_b64 exec, exec, s[4:5]
	s_cbranch_execz .LBB0_138

.LBB0_1464:
	s_waitcnt vmcnt(10)
	v_and_b32_e32 v131, 0xffff0000, v122
	v_and_b32_e32 v130, 0xffff0000, v98
	v_lshlrev_b32_e32 v125, 16, v122
	v_lshlrev_b32_e32 v124, 16, v98
	v_lshlrev_b32_e32 v158, 16, v99
	v_and_b32_e32 v122, 0xffff0000, v99
	v_pk_mul_f32 v[98:99], v[130:131], v[130:131]
	s_waitcnt vmcnt(2)
	v_and_b32_e32 v163, 0xffff0000, v128
	v_and_b32_e32 v162, 0xffff0000, v126
	v_lshlrev_b32_e32 v159, 16, v123
	v_pk_fma_f32 v[98:99], v[124:125], v[124:125], v[98:99]
	v_lshlrev_b32_e32 v161, 16, v128
	v_lshlrev_b32_e32 v160, 16, v126
	v_pk_mul_f32 v[100:101], v[162:163], v[162:163]
	v_and_b32_e32 v123, 0xffff0000, v123
	v_pk_fma_f32 v[98:99], v[158:159], v[158:159], v[98:99]
	v_lshlrev_b32_e32 v165, 16, v129
	v_lshlrev_b32_e32 v164, 16, v127
	v_pk_fma_f32 v[100:101], v[160:161], v[160:161], v[100:101]
	v_pk_fma_f32 v[98:99], v[122:123], v[122:123], v[98:99]
	v_and_b32_e32 v129, 0xffff0000, v129
	v_and_b32_e32 v128, 0xffff0000, v127
	v_pk_fma_f32 v[100:101], v[164:165], v[164:165], v[100:101]
	v_add_f32_e32 v98, v98, v99
	v_pk_fma_f32 v[100:101], v[128:129], v[128:129], v[100:101]
	v_lshlrev_b64 v[126:127], 12, v[102:103]
	v_add_f32_e32 v98, v98, v100
	v_add_f32_e32 v98, v98, v101
	s_nop 1
	v_add_f32_dpp v250, v98, v98 quad_perm:[1,0,3,2] row_mask:0xf bank_mask:0xf
	s_nop 1
	v_add_f32_dpp v250, v250, v250 quad_perm:[2,3,0,1] row_mask:0xf bank_mask:0xf
	s_nop 1
	v_add_f32_dpp v250, v250, v250 row_half_mirror row_mask:0xf bank_mask:0xf
	s_nop 1
	v_add_f32_dpp v250, v250, v250 row_mirror row_mask:0xf bank_mask:0xf
	v_mov_b32_e32 v251, v250
	v_mov_b32_e32 v252, v250
	s_nop 1
	v_permlane16_swap_b32_e32 v251, v252
	v_add_f32_e32 v250, v251, v252
	v_mov_b32_e32 v251, v250
	v_mov_b32_e32 v252, v250
	s_nop 1
	v_permlane32_swap_b32_e32 v251, v252
	v_mov_b32_e32 v101, v130
	v_mov_b32_e32 v130, v125
	v_lshl_add_u64 v[126:127], v[118:119], 0, v[126:127]
	s_waitcnt lgkmcnt(0)
	s_waitcnt lgkmcnt(0)
	s_waitcnt lgkmcnt(0)
	s_waitcnt lgkmcnt(0)
	s_waitcnt lgkmcnt(0)
	v_mov_b32_e32 v98, v158
	s_waitcnt lgkmcnt(0)
	v_add_f32_e32 v99, v251, v252
	v_fmamk_f32 v99, v99, 0x3a800000, v139
	v_mul_f32_e32 v100, 0x4b800000, v99
	v_cmp_gt_f32_e32 vcc, s56, v99
	s_nop 1
	v_cndmask_b32_e32 v99, v99, v100, vcc
	v_rsq_f32_e32 v106, v99
	v_mov_b32_e32 v99, v122
	v_mov_b32_e32 v100, v124
	v_mul_f32_e32 v122, 0x45800000, v106
	v_cndmask_b32_e32 v106, v106, v122, vcc
	v_pk_mul_f32 v[98:99], v[98:99], v[106:107] op_sel_hi:[1,0]
	v_pk_mul_f32 v[100:101], v[100:101], v[106:107] op_sel_hi:[1,0]
	v_pk_mul_f32 v[60:61], v[60:61], v[98:99]
	v_pk_mul_f32 v[58:59], v[58:59], v[100:101]
	v_mov_b32_e32 v122, v159
	v_pk_fma_f32 v[100:101], v[56:57], v[60:61], v[52:53]
	v_pk_fma_f32 v[98:99], v[54:55], v[58:59], v[50:51]
	v_pk_mul_f32 v[50:51], v[122:123], v[106:107] op_sel_hi:[1,0]
	v_pk_mul_f32 v[52:53], v[130:131], v[106:107] op_sel_hi:[1,0]
	v_pk_mul_f32 v[50:51], v[76:77], v[50:51]
	v_pk_mul_f32 v[54:55], v[74:75], v[52:53]
	v_pk_fma_f32 v[52:53], v[68:69], v[50:51], v[64:65]
	v_pk_fma_f32 v[50:51], v[66:67], v[54:55], v[62:63]
	v_mov_b32_e32 v54, v164
	v_mov_b32_e32 v55, v128
	v_mov_b32_e32 v56, v160
	v_mov_b32_e32 v57, v162
	v_pk_mul_f32 v[54:55], v[54:55], v[106:107] op_sel_hi:[1,0]
	v_pk_mul_f32 v[56:57], v[56:57], v[106:107] op_sel_hi:[1,0]
	v_pk_mul_f32 v[54:55], v[88:89], v[54:55]
	v_pk_mul_f32 v[58:59], v[86:87], v[56:57]
	v_mov_b32_e32 v128, v165
	v_mov_b32_e32 v162, v161
	v_pk_fma_f32 v[56:57], v[80:81], v[54:55], v[72:73]
	v_pk_fma_f32 v[54:55], v[78:79], v[58:59], v[70:71]
	v_pk_mul_f32 v[58:59], v[128:129], v[106:107] op_sel_hi:[1,0]
	v_pk_mul_f32 v[60:61], v[162:163], v[106:107] op_sel_hi:[1,0]
	s_waitcnt vmcnt(0)
	v_pk_mul_f32 v[58:59], v[96:97], v[58:59]
	v_pk_mul_f32 v[62:63], v[94:95], v[60:61]
	v_pk_fma_f32 v[60:61], v[92:93], v[58:59], v[84:85]
	v_pk_fma_f32 v[58:59], v[90:91], v[62:63], v[82:83]
	s_and_b64 vcc, exec, s[0:1]
	global_store_dwordx4 v[126:127], v[98:101], off
	global_store_dwordx4 v[126:127], v[50:53], off offset:1024
	global_store_dwordx4 v[126:127], v[54:57], off offset:2048
	global_store_dwordx4 v[126:127], v[58:61], off offset:3072
	s_cbranch_vccnz .LBB0_1447
	v_mov_b32_e32 v64, v99
	v_mov_b32_e32 v65, v51
	v_mov_b32_e32 v62, v98
	v_mov_b32_e32 v63, v50
	v_pk_mul_f32 v[64:65], v[64:65], v[64:65]
	v_mov_b32_e32 v66, v59
	v_pk_fma_f32 v[62:63], v[62:63], v[62:63], v[64:65]
	v_mov_b32_e32 v64, v100
	v_mov_b32_e32 v65, v52
	v_pk_fma_f32 v[62:63], v[64:65], v[64:65], v[62:63]
	v_mov_b32_e32 v64, v101
	v_mov_b32_e32 v65, v53
	v_mov_b32_e32 v67, v55
	v_pk_fma_f32 v[62:63], v[64:65], v[64:65], v[62:63]
	v_mov_b32_e32 v64, v58
	v_mov_b32_e32 v65, v54
	v_pk_mul_f32 v[66:67], v[66:67], v[66:67]
	v_add_f32_e32 v62, v62, v63
	v_pk_fma_f32 v[64:65], v[64:65], v[64:65], v[66:67]
	v_mov_b32_e32 v66, v60
	v_mov_b32_e32 v67, v56
	v_pk_fma_f32 v[64:65], v[66:67], v[66:67], v[64:65]
	v_mov_b32_e32 v66, v61
	v_mov_b32_e32 v67, v57
	v_pk_fma_f32 v[64:65], v[66:67], v[66:67], v[64:65]
	v_pk_add_f32 v[68:69], v[24:25], 1.0 op_sel_hi:[1,0]
	v_add_f32_e32 v62, v65, v62
	v_add_f32_e32 v62, v64, v62
	s_nop 1
	v_add_f32_dpp v250, v62, v62 quad_perm:[1,0,3,2] row_mask:0xf bank_mask:0xf
	s_nop 1
	v_add_f32_dpp v250, v250, v250 quad_perm:[2,3,0,1] row_mask:0xf bank_mask:0xf
	s_nop 1
	v_add_f32_dpp v250, v250, v250 row_half_mirror row_mask:0xf bank_mask:0xf
	s_nop 1
	v_add_f32_dpp v250, v250, v250 row_mirror row_mask:0xf bank_mask:0xf
	v_mov_b32_e32 v251, v250
	v_mov_b32_e32 v252, v250
	s_nop 1
	v_permlane16_swap_b32_e32 v251, v252
	v_add_f32_e32 v250, v251, v252
	v_mov_b32_e32 v251, v250
	v_mov_b32_e32 v252, v250
	s_nop 1
	v_permlane32_swap_b32_e32 v251, v252
	v_pk_add_f32 v[70:71], v[22:23], 1.0 op_sel_hi:[1,0]
	s_waitcnt lgkmcnt(0)
	s_waitcnt lgkmcnt(0)
	s_waitcnt lgkmcnt(0)
	s_waitcnt lgkmcnt(0)
	s_waitcnt lgkmcnt(0)
	s_waitcnt lgkmcnt(0)
	v_add_f32_e32 v62, v251, v252
	v_fmamk_f32 v62, v62, 0x3a800000, v139
	v_cmp_gt_f32_e32 vcc, s56, v62
	v_mul_f32_e32 v63, 0x4b800000, v62
	s_nop 0
	v_cndmask_b32_e32 v62, v62, v63, vcc
	v_rsq_f32_e32 v62, v62
	s_nop 0
	v_mul_f32_e32 v63, 0x45800000, v62
	v_cndmask_b32_e32 v62, v62, v63, vcc
	v_pk_mul_f32 v[64:65], v[100:101], v[62:63] op_sel_hi:[1,0]
	v_pk_mul_f32 v[66:67], v[98:99], v[62:63] op_sel_hi:[1,0]
	v_pk_mul_f32 v[64:65], v[40:41], v[64:65]
	v_pk_mul_f32 v[66:67], v[38:39], v[66:67]
	v_pk_fma_f32 v[64:65], v[68:69], v[64:65], v[8:9]
	v_pk_fma_f32 v[66:67], v[70:71], v[66:67], v[6:7]
	v_pk_mul_f32 v[52:53], v[52:53], v[62:63] op_sel_hi:[1,0]
	v_cvt_pk_bf16_f32 v66, v66, v67
	v_cvt_pk_bf16_f32 v67, v64, v65
	v_mad_u64_u32 v[64:65], s[0:1], v102, s58, v[120:121]
	v_mov_b32_e32 v68, v65
	v_mad_u64_u32 v[68:69], s[0:1], v103, s58, v[68:69]
	v_mov_b32_e32 v65, v68
	v_pk_mul_f32 v[50:51], v[50:51], v[62:63] op_sel_hi:[1,0]
	global_store_dwordx2 v[64:65], v[66:67], off
	v_pk_mul_f32 v[50:51], v[46:47], v[50:51]
	v_pk_mul_f32 v[52:53], v[48:49], v[52:53]
	v_pk_add_f32 v[66:67], v[32:33], 1.0 op_sel_hi:[1,0]
	v_pk_add_f32 v[68:69], v[30:31], 1.0 op_sel_hi:[1,0]
	v_pk_fma_f32 v[52:53], v[66:67], v[52:53], v[16:17]
	v_pk_fma_f32 v[50:51], v[68:69], v[50:51], v[14:15]
	s_nop 0
	v_cvt_pk_bf16_f32 v50, v50, v51
	v_cvt_pk_bf16_f32 v51, v52, v53
	global_store_dwordx2 v[64:65], v[50:51], off offset:512
	v_pk_mul_f32 v[50:51], v[56:57], v[62:63] op_sel_hi:[1,0]
	v_pk_mul_f32 v[52:53], v[54:55], v[62:63] op_sel_hi:[1,0]
	v_pk_mul_f32 v[50:51], v[44:45], v[50:51]
	v_pk_mul_f32 v[52:53], v[42:43], v[52:53]
	v_pk_add_f32 v[54:55], v[28:29], 1.0 op_sel_hi:[1,0]
	v_pk_add_f32 v[56:57], v[26:27], 1.0 op_sel_hi:[1,0]
	v_pk_fma_f32 v[50:51], v[54:55], v[50:51], v[12:13]
	v_pk_fma_f32 v[52:53], v[56:57], v[52:53], v[10:11]
	v_pk_add_f32 v[54:55], v[20:21], 1.0 op_sel_hi:[1,0]
	v_cvt_pk_bf16_f32 v52, v52, v53
	v_cvt_pk_bf16_f32 v53, v50, v51
	global_store_dwordx2 v[64:65], v[52:53], off offset:1024
	v_pk_mul_f32 v[50:51], v[60:61], v[62:63] op_sel_hi:[1,0]
	v_pk_mul_f32 v[52:53], v[58:59], v[62:63] op_sel_hi:[1,0]
	v_pk_mul_f32 v[50:51], v[36:37], v[50:51]
	v_pk_mul_f32 v[52:53], v[34:35], v[52:53]
	v_pk_add_f32 v[56:57], v[18:19], 1.0 op_sel_hi:[1,0]
	v_pk_fma_f32 v[50:51], v[54:55], v[50:51], v[4:5]
	v_pk_fma_f32 v[52:53], v[56:57], v[52:53], v[2:3]
	s_nop 0
	v_cvt_pk_bf16_f32 v52, v52, v53
	v_cvt_pk_bf16_f32 v53, v50, v51
	global_store_dwordx2 v[64:65], v[52:53], off offset:1536
	s_branch .LBB0_1447
